# weight conversion: 32 per-k norm-gain loads issued up front (was a depth-2 load/wait/mul chain); census counter loads batched
# baseline (speedup 1.0000x reference)
; #define LAS __attribute__((address_space(3)))
; __device__ __forceinline__ void conv_item(const float* W, int K, int Nsrc, int Ndst, const float* ksc, bf16* WT, int map, int item, LAS float* scr, int lane) {
;     const int nblk = Ndst / 32, kb = item / nblk, nb = item % nblk, k0 = 64 * kb, n0 = 32 * nb;
;     const int sc = src_col(map, n0 + (lane & 31));
;     float wv[32];
;     { const float* wp = W + (size_t)(k0 + (lane >> 5)) * Nsrc + (sc >= 0 ? sc : 0);
; #pragma unroll
;       for (int i = 0; i < 32; ++i) wv[i] = wp[(size_t)(2 * i) * Nsrc]; }
;     if (ksc) {
; #pragma unroll
;         for (int i = 0; i < 32; ++i) wv[i] *= ksc[k0 + 2 * i + (lane >> 5)];
.LBB0_455:
	s_andn2_b64 vcc, exec, s[0:1]
	s_cbranch_vccnz .LBB0_457
	s_add_i32 s0, s50, 0xffffec70
	s_lshr_b32 s1, s0, 1
	s_and_b32 s1, s1, 0x7fc0
	v_ashrrev_i32_e32 v9, 5, v7
	s_lshl_b32 s0, s0, 5
	v_add_u32_e32 v2, s1, v9
	s_and_b32 s0, s0, 0xfe0
	v_and_b32_e32 v8, 31, v7
	v_ashrrev_i32_e32 v3, 31, v2
	v_or_b32_e32 v0, s0, v8
	v_lshlrev_b64 v[4:5], 14, v[2:3]
	v_lshl_add_u64 v[4:5], s[28:29], 0, v[4:5]
	v_lshlrev_b32_e32 v0, 2, v0
	v_lshl_add_u64 v[4:5], v[4:5], 0, v[0:1]
	s_mov_b32 s27, 0x8000
	v_add_co_u32_e32 v10, vcc, s27, v4
	s_mov_b32 s27, 0x10000
	s_nop 0
	v_addc_co_u32_e32 v11, vcc, 0, v5, vcc
	global_load_dword v0, v[4:5], off
	global_load_dword v12, v[10:11], off
	v_add_co_u32_e32 v10, vcc, s27, v4
	s_mov_b32 s27, 0x18000
	s_nop 0
	v_addc_co_u32_e32 v11, vcc, 0, v5, vcc
	global_load_dword v13, v[10:11], off
	v_add_co_u32_e32 v10, vcc, s27, v4
	s_mov_b32 s27, 0x28000
	s_nop 0
	v_addc_co_u32_e32 v11, vcc, 0, v5, vcc
	global_load_dword v14, v[10:11], off
	v_add_co_u32_e32 v10, vcc, s36, v4
	s_mov_b32 s44, 0xe8000
	s_nop 0
	v_addc_co_u32_e32 v11, vcc, 0, v5, vcc
	global_load_dword v15, v[10:11], off
	v_add_co_u32_e32 v10, vcc, s27, v4
	s_mov_b32 s27, 0x30000
	s_nop 0
	v_addc_co_u32_e32 v11, vcc, 0, v5, vcc
	global_load_dword v16, v[10:11], off
	v_add_co_u32_e32 v10, vcc, s27, v4
	s_mov_b32 s27, 0x38000
	s_nop 0
	v_addc_co_u32_e32 v11, vcc, 0, v5, vcc
	global_load_dword v17, v[10:11], off
	v_add_co_u32_e32 v10, vcc, s27, v4
	s_mov_b32 s27, 0x40000
	s_nop 0
	v_addc_co_u32_e32 v11, vcc, 0, v5, vcc
	global_load_dword v18, v[10:11], off
	v_add_co_u32_e32 v10, vcc, s27, v4
	s_mov_b32 s27, 0x48000
	s_nop 0
	v_addc_co_u32_e32 v11, vcc, 0, v5, vcc
	global_load_dword v19, v[10:11], off
	v_add_co_u32_e32 v10, vcc, s27, v4
	s_mov_b32 s27, 0x50000
	s_nop 0
	v_addc_co_u32_e32 v11, vcc, 0, v5, vcc
	global_load_dword v20, v[10:11], off
	v_add_co_u32_e32 v10, vcc, s27, v4
	s_mov_b32 s27, 0x58000
	s_nop 0
	v_addc_co_u32_e32 v11, vcc, 0, v5, vcc
	global_load_dword v21, v[10:11], off
	v_add_co_u32_e32 v10, vcc, s27, v4
	s_mov_b32 s27, 0x60000
	s_nop 0
	v_addc_co_u32_e32 v11, vcc, 0, v5, vcc
	global_load_dword v22, v[10:11], off
	v_add_co_u32_e32 v10, vcc, s27, v4
	s_mov_b32 s27, 0x68000
	s_nop 0
	v_addc_co_u32_e32 v11, vcc, 0, v5, vcc
	global_load_dword v23, v[10:11], off
	v_add_co_u32_e32 v10, vcc, s27, v4
	s_mov_b32 s27, 0x70000
	s_nop 0
	v_addc_co_u32_e32 v11, vcc, 0, v5, vcc
	global_load_dword v24, v[10:11], off
	v_add_co_u32_e32 v10, vcc, s27, v4
	s_mov_b32 s27, 0x78000
	s_nop 0
	v_addc_co_u32_e32 v11, vcc, 0, v5, vcc
	global_load_dword v25, v[10:11], off
	v_add_co_u32_e32 v10, vcc, s27, v4
	s_mov_b32 s27, 0x80000
	s_nop 0
	v_addc_co_u32_e32 v11, vcc, 0, v5, vcc
	global_load_dword v26, v[10:11], off
	v_add_co_u32_e32 v10, vcc, s27, v4
	s_mov_b32 s27, 0x88000
	s_nop 0
	v_addc_co_u32_e32 v11, vcc, 0, v5, vcc
	global_load_dword v27, v[10:11], off
	v_add_co_u32_e32 v10, vcc, s27, v4
	s_mov_b32 s27, 0x90000
	s_nop 0
	v_addc_co_u32_e32 v11, vcc, 0, v5, vcc
	global_load_dword v28, v[10:11], off
	v_add_co_u32_e32 v10, vcc, s27, v4
	s_mov_b32 s27, 0x98000
	s_nop 0
	v_addc_co_u32_e32 v11, vcc, 0, v5, vcc
	global_load_dword v29, v[10:11], off
	v_add_co_u32_e32 v10, vcc, s27, v4
	s_mov_b32 s27, 0xa0000
	s_nop 0
	v_addc_co_u32_e32 v11, vcc, 0, v5, vcc
	global_load_dword v30, v[10:11], off
	v_add_co_u32_e32 v10, vcc, s27, v4
	s_mov_b32 s27, 0xa8000
	s_nop 0
	v_addc_co_u32_e32 v11, vcc, 0, v5, vcc
	global_load_dword v31, v[10:11], off
	v_add_co_u32_e32 v10, vcc, s27, v4
	s_mov_b32 s27, 0xb0000
	s_nop 0
	v_addc_co_u32_e32 v11, vcc, 0, v5, vcc
	global_load_dword v32, v[10:11], off
	v_add_co_u32_e32 v10, vcc, s27, v4
	s_mov_b32 s27, 0xb8000
	s_nop 0
	v_addc_co_u32_e32 v11, vcc, 0, v5, vcc
	global_load_dword v33, v[10:11], off
	v_add_co_u32_e32 v10, vcc, s27, v4
	s_mov_b32 s27, 0xc0000
	s_nop 0
	v_addc_co_u32_e32 v11, vcc, 0, v5, vcc
	global_load_dword v34, v[10:11], off
	v_add_co_u32_e32 v10, vcc, s27, v4
	s_mov_b32 s27, 0xc8000
	s_nop 0
	v_addc_co_u32_e32 v11, vcc, 0, v5, vcc
	global_load_dword v35, v[10:11], off
	v_add_co_u32_e32 v10, vcc, s27, v4
	s_mov_b32 s27, 0xd0000
	s_nop 0
	v_addc_co_u32_e32 v11, vcc, 0, v5, vcc
	global_load_dword v36, v[10:11], off
	v_add_co_u32_e32 v10, vcc, s27, v4
	s_mov_b32 s27, 0xd8000
	s_nop 0
	v_addc_co_u32_e32 v11, vcc, 0, v5, vcc
	global_load_dword v37, v[10:11], off
	v_add_co_u32_e32 v10, vcc, s27, v4
	s_mov_b32 s27, 0xe0000
	s_nop 0
	v_addc_co_u32_e32 v11, vcc, 0, v5, vcc
	global_load_dword v38, v[10:11], off
	v_add_co_u32_e32 v10, vcc, s27, v4
	v_lshl_add_u64 v[2:3], v[2:3], 2, s[46:47]
	s_nop 0
	v_addc_co_u32_e32 v11, vcc, 0, v5, vcc
	global_load_dword v39, v[10:11], off
	v_add_co_u32_e32 v10, vcc, s44, v4
	s_mov_b32 s44, 0xf0000
	s_nop 0
	v_addc_co_u32_e32 v11, vcc, 0, v5, vcc
	global_load_dword v40, v[10:11], off
	v_add_co_u32_e32 v10, vcc, s44, v4
	s_mov_b32 s44, 0xf8000
	s_nop 0
	v_addc_co_u32_e32 v11, vcc, 0, v5, vcc
	v_add_co_u32_e32 v4, vcc, s44, v4
	global_load_dword v10, v[10:11], off
	s_nop 0
	v_addc_co_u32_e32 v5, vcc, 0, v5, vcc
	global_load_dword v4, v[4:5], off
	s_movk_i32 s27, 0x84
	global_load_dword v64, v[2:3], off
	global_load_dword v65, v[2:3], off offset:16
	global_load_dword v66, v[2:3], off offset:8
	global_load_dword v67, v[2:3], off offset:32
	global_load_dword v68, v[2:3], off offset:24
	global_load_dword v69, v[2:3], off offset:48
	global_load_dword v70, v[2:3], off offset:40
	global_load_dword v71, v[2:3], off offset:64
	global_load_dword v72, v[2:3], off offset:56
	global_load_dword v73, v[2:3], off offset:80
	global_load_dword v74, v[2:3], off offset:72
	global_load_dword v75, v[2:3], off offset:96
	global_load_dword v76, v[2:3], off offset:88
	global_load_dword v77, v[2:3], off offset:112
	global_load_dword v78, v[2:3], off offset:104
	global_load_dword v79, v[2:3], off offset:128
	global_load_dword v80, v[2:3], off offset:120
	global_load_dword v81, v[2:3], off offset:144
	global_load_dword v82, v[2:3], off offset:136
	global_load_dword v83, v[2:3], off offset:160
	global_load_dword v84, v[2:3], off offset:152
	global_load_dword v85, v[2:3], off offset:176
	global_load_dword v86, v[2:3], off offset:168
	global_load_dword v87, v[2:3], off offset:192
	global_load_dword v88, v[2:3], off offset:184
	global_load_dword v89, v[2:3], off offset:208
	global_load_dword v90, v[2:3], off offset:200
	global_load_dword v91, v[2:3], off offset:224
	global_load_dword v92, v[2:3], off offset:216
	global_load_dword v93, v[2:3], off offset:240
	global_load_dword v94, v[2:3], off offset:232
	global_load_dword v95, v[2:3], off offset:248
	s_lshl_b32 s1, s1, 1
	s_add_u32 s52, s58, s1
	s_addc_u32 s53, s59, 0
	s_waitcnt vmcnt(31)
; #define LAS __attribute__((address_space(3)))
; __device__ __forceinline__ unsigned pk2(float lo, float hi) { f32x2 v = {lo, hi}; bf16x2_t b = __builtin_convertvector(v, bf16x2_t); return __builtin_bit_cast(unsigned, b); }
; __device__ __forceinline__ void conv_item(const float* W, int K, int Nsrc, int Ndst, const float* ksc, bf16* WT, int map, int item, LAS float* scr, int lane) {
;     ...
;         for (int i = 0; i < 32; ++i) wv[i] *= ksc[k0 + 2 * i + (lane >> 5)];
;     }
; #pragma unroll
;     for (int i = 0; i < 32; ++i) scr[(2 * i + (lane >> 5)) * 33 + (lane & 31)] = (sc >= 0) ? wv[i] : 0.f;
;     asm volatile("s_waitcnt lgkmcnt(0)" ::: "memory");
;     const int c = lane & 7;
; #pragma unroll
;     for (int j = 0; j < 4; ++j) { const int n = (lane >> 3) + 8 * j; const LAS float* s = scr + (8 * c) * 33 + n;
;         u32x4 o; o.x = pk2(s[0 * 33], s[1 * 33]); o.y = pk2(s[2 * 33], s[3 * 33]); o.z = pk2(s[4 * 33], s[5 * 33]); o.w = pk2(s[6 * 33], s[7 * 33]);
;         *(u32x4*)(WT + (size_t)(n0 + n) * K + k0 + 8 * c) = o; }
;     asm volatile("s_waitcnt lgkmcnt(0)" ::: "memory");
	v_mul_f32_e32 v0, v0, v64
	s_waitcnt vmcnt(30)
	v_mul_f32_e32 v11, v13, v65
	s_waitcnt vmcnt(29)
	v_mul_f32_e32 v5, v12, v66
	s_waitcnt vmcnt(28)
	v_mul_f32_e32 v13, v15, v67
	s_waitcnt vmcnt(27)
	v_mul_f32_e32 v12, v14, v68
	s_waitcnt vmcnt(26)
	v_mul_f32_e32 v15, v17, v69
	s_waitcnt vmcnt(25)
	v_mul_f32_e32 v14, v16, v70
	s_waitcnt vmcnt(24)
	v_mul_f32_e32 v17, v19, v71
	s_waitcnt vmcnt(23)
	v_mul_f32_e32 v16, v18, v72
	s_waitcnt vmcnt(22)
	v_mul_f32_e32 v19, v21, v73
	s_waitcnt vmcnt(21)
	v_mul_f32_e32 v18, v20, v74
	s_waitcnt vmcnt(20)
	v_mul_f32_e32 v21, v23, v75
	s_waitcnt vmcnt(19)
	v_mul_f32_e32 v20, v22, v76
	s_waitcnt vmcnt(18)
	v_mul_f32_e32 v23, v25, v77
	s_waitcnt vmcnt(17)
	v_mul_f32_e32 v22, v24, v78
	s_waitcnt vmcnt(16)
	v_mul_f32_e32 v25, v27, v79
	s_waitcnt vmcnt(15)
	v_mul_f32_e32 v24, v26, v80
	s_waitcnt vmcnt(14)
	v_mul_f32_e32 v27, v29, v81
	s_waitcnt vmcnt(13)
	v_mul_f32_e32 v26, v28, v82
	s_waitcnt vmcnt(12)
	v_mul_f32_e32 v29, v31, v83
	s_waitcnt vmcnt(11)
	v_mul_f32_e32 v28, v30, v84
	s_waitcnt vmcnt(10)
	v_mul_f32_e32 v31, v33, v85
	s_waitcnt vmcnt(9)
	v_mul_f32_e32 v30, v32, v86
	s_waitcnt vmcnt(8)
	v_mul_f32_e32 v33, v35, v87
	s_waitcnt vmcnt(7)
	v_mul_f32_e32 v32, v34, v88
	s_waitcnt vmcnt(6)
	v_mul_f32_e32 v35, v37, v89
	s_waitcnt vmcnt(5)
	v_mul_f32_e32 v34, v36, v90
	s_waitcnt vmcnt(4)
	v_mul_f32_e32 v37, v39, v91
	s_waitcnt vmcnt(3)
	v_mul_f32_e32 v36, v38, v92
	s_waitcnt vmcnt(2)
	v_mul_f32_e32 v10, v10, v93
	v_lshlrev_b32_e32 v3, 2, v8
	s_waitcnt vmcnt(1)
	v_mul_f32_e32 v38, v40, v94
	s_waitcnt vmcnt(0)
	v_mul_f32_e32 v2, v4, v95
	v_mul_lo_u32 v4, v9, s27
	v_add3_u32 v3, s56, v3, v4
	ds_write2_b32 v3, v0, v5 offset1:66
	ds_write2_b32 v3, v11, v12 offset0:132 offset1:198
	v_add_u32_e32 v0, 0x400, v3
	ds_write2_b32 v0, v13, v14 offset0:8 offset1:74
	ds_write2_b32 v0, v15, v16 offset0:140 offset1:206
	v_add_u32_e32 v0, 0x800, v3
	ds_write2_b32 v0, v17, v18 offset0:16 offset1:82
	ds_write2_b32 v0, v19, v20 offset0:148 offset1:214
	v_add_u32_e32 v0, 0xc00, v3
	ds_write2_b32 v0, v21, v22 offset0:24 offset1:90
	ds_write2_b32 v0, v23, v24 offset0:156 offset1:222
	v_add_u32_e32 v0, 0x1000, v3
	ds_write2_b32 v0, v25, v26 offset0:32 offset1:98
	ds_write2_b32 v0, v27, v28 offset0:164 offset1:230
	v_add_u32_e32 v0, 0x1400, v3
	ds_write2_b32 v0, v29, v30 offset0:40 offset1:106
	ds_write2_b32 v0, v31, v32 offset0:172 offset1:238
	v_add_u32_e32 v0, 0x1800, v3
	ds_write2_b32 v0, v33, v34 offset0:48 offset1:114
	ds_write2_b32 v0, v35, v36 offset0:180 offset1:246
	v_add_u32_e32 v0, 0x1c00, v3
	ds_write2_b32 v0, v37, v38 offset0:56 offset1:122
	ds_write2_b32 v0, v10, v2 offset0:188 offset1:254
	v_lshlrev_b32_e32 v0, 3, v7
	v_and_b32_e32 v0, 56, v0
	v_ashrrev_i32_e32 v26, 3, v7
	v_mul_u32_u24_e32 v4, 0x84, v0
	v_lshlrev_b32_e32 v0, 1, v0
	v_lshl_add_u64 v[2:3], s[52:53], 0, v[0:1]
	v_lshlrev_b32_e32 v0, 2, v26
	s_waitcnt lgkmcnt(0)
	v_add3_u32 v0, s56, v4, v0
	ds_read2_b32 v[10:11], v0 offset0:33 offset1:41
	ds_read2_b32 v[12:13], v0 offset1:8
	ds_read2_b32 v[14:15], v0 offset0:66 offset1:74
	ds_read2_b32 v[16:17], v0 offset0:99 offset1:107
	ds_read2_b32 v[18:19], v0 offset0:132 offset1:140
	ds_read2_b32 v[20:21], v0 offset0:165 offset1:173
	ds_read2_b32 v[22:23], v0 offset0:198 offset1:206
	ds_read2_b32 v[24:25], v0 offset0:231 offset1:239
	v_add_u32_e32 v26, s0, v26
	s_mov_b64 s[52:53], 0x1c00000
	v_ashrrev_i32_e32 v27, 31, v26
	v_lshl_add_u64 v[8:9], v[2:3], 0, s[52:53]
	v_lshlrev_b64 v[28:29], 11, v[26:27]
	s_waitcnt lgkmcnt(6)
	v_cvt_pk_bf16_f32 v2, v12, v10
	s_waitcnt lgkmcnt(4)
	v_cvt_pk_bf16_f32 v3, v14, v16
	s_waitcnt lgkmcnt(2)
	v_cvt_pk_bf16_f32 v4, v18, v20
	s_waitcnt lgkmcnt(0)
	v_cvt_pk_bf16_f32 v5, v22, v24
	v_lshl_add_u64 v[28:29], v[8:9], 0, v[28:29]
	v_add_u32_e32 v10, 8, v26
	global_store_dwordx4 v[28:29], v[2:5], off
	v_add_u32_e32 v28, 16, v26
	v_ashrrev_i32_e32 v29, 31, v28
	v_cvt_pk_bf16_f32 v2, v13, v11
	v_ashrrev_i32_e32 v11, 31, v10
	v_lshlrev_b64 v[10:11], 11, v[10:11]
	v_cvt_pk_bf16_f32 v3, v15, v17
	v_cvt_pk_bf16_f32 v4, v19, v21
	v_cvt_pk_bf16_f32 v5, v23, v25
	v_lshl_add_u64 v[10:11], v[8:9], 0, v[10:11]
	global_store_dwordx4 v[10:11], v[2:5], off
	ds_read2_b32 v[10:11], v0 offset0:49 offset1:57
	ds_read2_b32 v[12:13], v0 offset0:16 offset1:24
	ds_read2_b32 v[14:15], v0 offset0:82 offset1:90
	ds_read2_b32 v[16:17], v0 offset0:115 offset1:123
	ds_read2_b32 v[18:19], v0 offset0:148 offset1:156
	ds_read2_b32 v[20:21], v0 offset0:181 offset1:189
	ds_read2_b32 v[22:23], v0 offset0:214 offset1:222
	ds_read2_b32 v[24:25], v0 offset0:247 offset1:255
	v_lshlrev_b64 v[28:29], 11, v[28:29]
	s_waitcnt lgkmcnt(6)
	v_cvt_pk_bf16_f32 v2, v12, v10
	s_waitcnt lgkmcnt(4)
	v_cvt_pk_bf16_f32 v3, v14, v16
	s_waitcnt lgkmcnt(2)
	v_cvt_pk_bf16_f32 v4, v18, v20
	s_waitcnt lgkmcnt(0)
	v_cvt_pk_bf16_f32 v5, v22, v24
	v_lshl_add_u64 v[28:29], v[8:9], 0, v[28:29]
	v_add_u32_e32 v10, 24, v26
	global_store_dwordx4 v[28:29], v[2:5], off
	s_nop 1
	v_cvt_pk_bf16_f32 v2, v13, v11
	v_ashrrev_i32_e32 v11, 31, v10
	v_lshlrev_b64 v[10:11], 11, v[10:11]
	v_cvt_pk_bf16_f32 v3, v15, v17
	v_cvt_pk_bf16_f32 v4, v19, v21
	v_cvt_pk_bf16_f32 v5, v23, v25
	v_lshl_add_u64 v[8:9], v[8:9], 0, v[10:11]
	global_store_dwordx4 v[8:9], v[2:5], off
	s_waitcnt lgkmcnt(0)

; __device__ __forceinline__ void conv_item(const float* W, int K, int Nsrc, int Ndst, const float* ksc, bf16* WT, int map, int item, LAS float* scr, int lane) {
;     ...
;     const int sc = src_col(map, n0 + (lane & 31));
;     float wv[32];
;     { const float* wp = W + (size_t)(k0 + (lane >> 5)) * Nsrc + (sc >= 0 ? sc : 0);
; #pragma unroll
;       for (int i = 0; i < 32; ++i) wv[i] = wp[(size_t)(2 * i) * Nsrc]; }
;     if (ksc) {
; #pragma unroll
;         for (int i = 0; i < 32; ++i) wv[i] *= ksc[k0 + 2 * i + (lane >> 5)];
.LBB0_469:
	s_lshl_b32 s0, s51, 1
	s_and_b32 s0, s0, 0x1c0
	v_ashrrev_i32_e32 v9, 5, v7
	v_add_u32_e32 v2, s0, v9
	v_ashrrev_i32_e32 v3, 31, v2
	v_lshlrev_b64 v[4:5], 12, v[2:3]
	v_lshl_add_u64 v[4:5], s[30:31], 0, v[4:5]
	v_lshl_add_u64 v[4:5], v[0:1], 2, v[4:5]
	v_add_co_u32_e32 v10, vcc, 0x2000, v4
	s_movk_i32 s1, 0x4000
	s_nop 0
	v_addc_co_u32_e32 v11, vcc, 0, v5, vcc
	global_load_dword v0, v[4:5], off
	global_load_dword v12, v[10:11], off
	v_add_co_u32_e32 v10, vcc, s1, v4
	s_mov_b32 s1, 0x8000
	s_nop 0
	v_addc_co_u32_e32 v11, vcc, 0, v5, vcc
	global_load_dword v13, v[10:11], off
	v_add_co_u32_e32 v10, vcc, 0x6000, v4
	v_lshl_add_u64 v[2:3], v[2:3], 2, s[38:39]
	s_nop 0
	v_addc_co_u32_e32 v11, vcc, 0, v5, vcc
	global_load_dword v14, v[10:11], off
	v_add_co_u32_e32 v10, vcc, s1, v4
	s_mov_b32 s1, 0x30000
	s_nop 0
	v_addc_co_u32_e32 v11, vcc, 0, v5, vcc
	global_load_dword v15, v[10:11], off
	v_add_co_u32_e32 v10, vcc, 0xa000, v4
	s_lshl_b32 s0, s0, 1
	s_nop 0
	v_addc_co_u32_e32 v11, vcc, 0, v5, vcc
	global_load_dword v16, v[10:11], off
	v_add_co_u32_e32 v10, vcc, 0xc000, v4
	s_add_u32 s0, s58, s0
	s_nop 0
	v_addc_co_u32_e32 v11, vcc, 0, v5, vcc
	global_load_dword v17, v[10:11], off
	v_add_co_u32_e32 v10, vcc, 0xe000, v4
	s_nop 1
	v_addc_co_u32_e32 v11, vcc, 0, v5, vcc
	global_load_dword v18, v[10:11], off
	v_add_co_u32_e32 v10, vcc, 0x10000, v4
	s_nop 1
	v_addc_co_u32_e32 v11, vcc, 0, v5, vcc
	global_load_dword v19, v[10:11], off
	v_add_co_u32_e32 v10, vcc, 0x12000, v4
	s_nop 1
	v_addc_co_u32_e32 v11, vcc, 0, v5, vcc
	global_load_dword v20, v[10:11], off
	v_add_co_u32_e32 v10, vcc, 0x14000, v4
	s_nop 1
	v_addc_co_u32_e32 v11, vcc, 0, v5, vcc
	global_load_dword v21, v[10:11], off
	v_add_co_u32_e32 v10, vcc, 0x16000, v4
	s_nop 1
	v_addc_co_u32_e32 v11, vcc, 0, v5, vcc
	global_load_dword v22, v[10:11], off
	v_add_co_u32_e32 v10, vcc, 0x18000, v4
	s_nop 1
	v_addc_co_u32_e32 v11, vcc, 0, v5, vcc
	global_load_dword v23, v[10:11], off
	v_add_co_u32_e32 v10, vcc, 0x1a000, v4
	s_nop 1
	v_addc_co_u32_e32 v11, vcc, 0, v5, vcc
	global_load_dword v24, v[10:11], off
	v_add_co_u32_e32 v10, vcc, 0x1c000, v4
	s_nop 1
	v_addc_co_u32_e32 v11, vcc, 0, v5, vcc
	global_load_dword v25, v[10:11], off
	v_add_co_u32_e32 v10, vcc, 0x1e000, v4
	s_nop 1
	v_addc_co_u32_e32 v11, vcc, 0, v5, vcc
	global_load_dword v26, v[10:11], off
	v_add_co_u32_e32 v10, vcc, 0x20000, v4
	s_nop 1
	v_addc_co_u32_e32 v11, vcc, 0, v5, vcc
	global_load_dword v27, v[10:11], off
	v_add_co_u32_e32 v10, vcc, 0x22000, v4
	s_nop 1
	v_addc_co_u32_e32 v11, vcc, 0, v5, vcc
	global_load_dword v28, v[10:11], off
	v_add_co_u32_e32 v10, vcc, 0x24000, v4
	s_nop 1
	v_addc_co_u32_e32 v11, vcc, 0, v5, vcc
	global_load_dword v29, v[10:11], off
	v_add_co_u32_e32 v10, vcc, 0x26000, v4
	s_nop 1
	v_addc_co_u32_e32 v11, vcc, 0, v5, vcc
	global_load_dword v30, v[10:11], off
	v_add_co_u32_e32 v10, vcc, 0x28000, v4
	s_nop 1
	v_addc_co_u32_e32 v11, vcc, 0, v5, vcc
	global_load_dword v31, v[10:11], off
	v_add_co_u32_e32 v10, vcc, 0x2a000, v4
	s_nop 1
	v_addc_co_u32_e32 v11, vcc, 0, v5, vcc
	global_load_dword v32, v[10:11], off
	v_add_co_u32_e32 v10, vcc, 0x2c000, v4
	s_nop 1
	v_addc_co_u32_e32 v11, vcc, 0, v5, vcc
	global_load_dword v33, v[10:11], off
	v_add_co_u32_e32 v10, vcc, 0x2e000, v4
	s_nop 1
	v_addc_co_u32_e32 v11, vcc, 0, v5, vcc
	global_load_dword v34, v[10:11], off
	v_add_co_u32_e32 v10, vcc, s1, v4
	s_movk_i32 s1, 0x84
	s_nop 0
	v_addc_co_u32_e32 v11, vcc, 0, v5, vcc
	global_load_dword v35, v[10:11], off
	v_add_co_u32_e32 v10, vcc, 0x32000, v4
	s_nop 1
	v_addc_co_u32_e32 v11, vcc, 0, v5, vcc
	global_load_dword v36, v[10:11], off
	v_add_co_u32_e32 v10, vcc, 0x34000, v4
	s_nop 1
	v_addc_co_u32_e32 v11, vcc, 0, v5, vcc
	global_load_dword v37, v[10:11], off
	v_add_co_u32_e32 v10, vcc, 0x36000, v4
	s_nop 1
	v_addc_co_u32_e32 v11, vcc, 0, v5, vcc
	global_load_dword v38, v[10:11], off
	v_add_co_u32_e32 v10, vcc, 0x38000, v4
	s_nop 1
	v_addc_co_u32_e32 v11, vcc, 0, v5, vcc
	global_load_dword v39, v[10:11], off
	v_add_co_u32_e32 v10, vcc, 0x3a000, v4
	s_nop 1
	v_addc_co_u32_e32 v11, vcc, 0, v5, vcc
	global_load_dword v40, v[10:11], off
	v_add_co_u32_e32 v10, vcc, 0x3c000, v4
	s_nop 1
	v_addc_co_u32_e32 v11, vcc, 0, v5, vcc
	v_add_co_u32_e32 v4, vcc, 0x3e000, v4
	global_load_dword v10, v[10:11], off
	s_nop 0
	v_addc_co_u32_e32 v5, vcc, 0, v5, vcc
	global_load_dword v4, v[4:5], off
	s_nop 0
	global_load_dword v64, v[2:3], off
	global_load_dword v65, v[2:3], off offset:16
	global_load_dword v66, v[2:3], off offset:8
	global_load_dword v67, v[2:3], off offset:32
	global_load_dword v68, v[2:3], off offset:24
	global_load_dword v69, v[2:3], off offset:48
	global_load_dword v70, v[2:3], off offset:40
	global_load_dword v71, v[2:3], off offset:64
	global_load_dword v72, v[2:3], off offset:56
	global_load_dword v73, v[2:3], off offset:80
	global_load_dword v74, v[2:3], off offset:72
	global_load_dword v75, v[2:3], off offset:96
	global_load_dword v76, v[2:3], off offset:88
	global_load_dword v77, v[2:3], off offset:112
	global_load_dword v78, v[2:3], off offset:104
	global_load_dword v79, v[2:3], off offset:128
	global_load_dword v80, v[2:3], off offset:120
	global_load_dword v81, v[2:3], off offset:144
	global_load_dword v82, v[2:3], off offset:136
	global_load_dword v83, v[2:3], off offset:160
	global_load_dword v84, v[2:3], off offset:152
	global_load_dword v85, v[2:3], off offset:176
	global_load_dword v86, v[2:3], off offset:168
	global_load_dword v87, v[2:3], off offset:192
	global_load_dword v88, v[2:3], off offset:184
	global_load_dword v89, v[2:3], off offset:208
	global_load_dword v90, v[2:3], off offset:200
	global_load_dword v91, v[2:3], off offset:224
	global_load_dword v92, v[2:3], off offset:216
	global_load_dword v93, v[2:3], off offset:240
	global_load_dword v94, v[2:3], off offset:232
	global_load_dword v95, v[2:3], off offset:248
	s_waitcnt vmcnt(31)
; #define LAS __attribute__((address_space(3)))
; __device__ __forceinline__ unsigned pk2(float lo, float hi) { f32x2 v = {lo, hi}; bf16x2_t b = __builtin_convertvector(v, bf16x2_t); return __builtin_bit_cast(unsigned, b); }
; __device__ __forceinline__ void conv_item(const float* W, int K, int Nsrc, int Ndst, const float* ksc, bf16* WT, int map, int item, LAS float* scr, int lane) {
;     ...
;         for (int i = 0; i < 32; ++i) wv[i] *= ksc[k0 + 2 * i + (lane >> 5)];
;     }
; #pragma unroll
;     for (int i = 0; i < 32; ++i) scr[(2 * i + (lane >> 5)) * 33 + (lane & 31)] = (sc >= 0) ? wv[i] : 0.f;
;     asm volatile("s_waitcnt lgkmcnt(0)" ::: "memory");
;     const int c = lane & 7;
; #pragma unroll
;     for (int j = 0; j < 4; ++j) { const int n = (lane >> 3) + 8 * j; const LAS float* s = scr + (8 * c) * 33 + n;
;         u32x4 o; o.x = pk2(s[0 * 33], s[1 * 33]); o.y = pk2(s[2 * 33], s[3 * 33]); o.z = pk2(s[4 * 33], s[5 * 33]); o.w = pk2(s[6 * 33], s[7 * 33]);
;         *(u32x4*)(WT + (size_t)(n0 + n) * K + k0 + 8 * c) = o; }
;     asm volatile("s_waitcnt lgkmcnt(0)" ::: "memory");
	v_mul_f32_e32 v0, v0, v64
	s_waitcnt vmcnt(30)
	v_mul_f32_e32 v11, v13, v65
	s_waitcnt vmcnt(29)
	v_mul_f32_e32 v5, v12, v66
	s_waitcnt vmcnt(28)
	v_mul_f32_e32 v13, v15, v67
	s_waitcnt vmcnt(27)
	v_mul_f32_e32 v12, v14, v68
	s_waitcnt vmcnt(26)
	v_mul_f32_e32 v15, v17, v69
	s_waitcnt vmcnt(25)
	v_mul_f32_e32 v14, v16, v70
	s_waitcnt vmcnt(24)
	v_mul_f32_e32 v17, v19, v71
	s_waitcnt vmcnt(23)
	v_mul_f32_e32 v16, v18, v72
	s_waitcnt vmcnt(22)
	v_mul_f32_e32 v19, v21, v73
	s_waitcnt vmcnt(21)
	v_mul_f32_e32 v18, v20, v74
	s_waitcnt vmcnt(20)
	v_mul_f32_e32 v21, v23, v75
	s_waitcnt vmcnt(19)
	v_mul_f32_e32 v20, v22, v76
	s_waitcnt vmcnt(18)
	v_mul_f32_e32 v23, v25, v77
	s_waitcnt vmcnt(17)
	v_mul_f32_e32 v22, v24, v78
	s_waitcnt vmcnt(16)
	v_mul_f32_e32 v25, v27, v79
	s_waitcnt vmcnt(15)
	v_mul_f32_e32 v24, v26, v80
	s_waitcnt vmcnt(14)
	v_mul_f32_e32 v27, v29, v81
	s_waitcnt vmcnt(13)
	v_mul_f32_e32 v26, v28, v82
	s_waitcnt vmcnt(12)
	v_mul_f32_e32 v29, v31, v83
	s_waitcnt vmcnt(11)
	v_mul_f32_e32 v28, v30, v84
	s_waitcnt vmcnt(10)
	v_mul_f32_e32 v31, v33, v85
	s_waitcnt vmcnt(9)
	v_mul_f32_e32 v30, v32, v86
	s_waitcnt vmcnt(8)
	v_mul_f32_e32 v33, v35, v87
	s_waitcnt vmcnt(7)
	v_mul_f32_e32 v32, v34, v88
	s_waitcnt vmcnt(6)
	v_mul_f32_e32 v35, v37, v89
	s_waitcnt vmcnt(5)
	v_mul_f32_e32 v34, v36, v90
	s_waitcnt vmcnt(4)
	v_mul_f32_e32 v37, v39, v91
	s_waitcnt vmcnt(3)
	v_mul_f32_e32 v36, v38, v92
	s_waitcnt vmcnt(2)
	v_mul_f32_e32 v10, v10, v93
	v_lshlrev_b32_e32 v3, 2, v8
	s_waitcnt vmcnt(1)
	v_mul_f32_e32 v38, v40, v94
	s_waitcnt vmcnt(0)
	v_mul_f32_e32 v2, v4, v95
	v_mul_lo_u32 v4, v9, s1
	v_add3_u32 v3, s56, v3, v4
	ds_write2_b32 v3, v0, v5 offset1:66
	ds_write2_b32 v3, v11, v12 offset0:132 offset1:198
	v_add_u32_e32 v0, 0x400, v3
	ds_write2_b32 v0, v13, v14 offset0:8 offset1:74
	ds_write2_b32 v0, v15, v16 offset0:140 offset1:206
	v_add_u32_e32 v0, 0x800, v3
	ds_write2_b32 v0, v17, v18 offset0:16 offset1:82
	ds_write2_b32 v0, v19, v20 offset0:148 offset1:214
	v_add_u32_e32 v0, 0xc00, v3
	ds_write2_b32 v0, v21, v22 offset0:24 offset1:90
	ds_write2_b32 v0, v23, v24 offset0:156 offset1:222
	v_add_u32_e32 v0, 0x1000, v3
	ds_write2_b32 v0, v25, v26 offset0:32 offset1:98
	ds_write2_b32 v0, v27, v28 offset0:164 offset1:230
	v_add_u32_e32 v0, 0x1400, v3
	ds_write2_b32 v0, v29, v30 offset0:40 offset1:106
	ds_write2_b32 v0, v31, v32 offset0:172 offset1:238
	v_add_u32_e32 v0, 0x1800, v3
	ds_write2_b32 v0, v33, v34 offset0:48 offset1:114
	ds_write2_b32 v0, v35, v36 offset0:180 offset1:246
	v_add_u32_e32 v0, 0x1c00, v3
	ds_write2_b32 v0, v37, v38 offset0:56 offset1:122
	ds_write2_b32 v0, v10, v2 offset0:188 offset1:254
	v_lshlrev_b32_e32 v0, 3, v7
	v_and_b32_e32 v0, 56, v0
	v_ashrrev_i32_e32 v26, 3, v7
	v_mul_u32_u24_e32 v4, 0x84, v0
	s_addc_u32 s1, s59, 0
	v_lshlrev_b32_e32 v0, 1, v0
	v_lshl_add_u64 v[2:3], s[0:1], 0, v[0:1]
	v_lshlrev_b32_e32 v0, 2, v26
	s_waitcnt lgkmcnt(0)
	v_add3_u32 v0, s56, v4, v0
	ds_read2_b32 v[10:11], v0 offset0:33 offset1:41
	ds_read2_b32 v[12:13], v0 offset1:8
	ds_read2_b32 v[14:15], v0 offset0:66 offset1:74
	ds_read2_b32 v[16:17], v0 offset0:99 offset1:107
	ds_read2_b32 v[18:19], v0 offset0:132 offset1:140
	ds_read2_b32 v[20:21], v0 offset0:165 offset1:173
	ds_read2_b32 v[22:23], v0 offset0:198 offset1:206
	ds_read2_b32 v[24:25], v0 offset0:231 offset1:239
	v_add_u32_e32 v26, s44, v26
	s_mov_b64 s[0:1], 0x1660000
	v_ashrrev_i32_e32 v27, 31, v26
	v_lshl_add_u64 v[8:9], v[2:3], 0, s[0:1]
	v_lshlrev_b64 v[28:29], 9, v[26:27]
	s_waitcnt lgkmcnt(6)
	v_cvt_pk_bf16_f32 v2, v12, v10
	s_waitcnt lgkmcnt(4)
	v_cvt_pk_bf16_f32 v3, v14, v16
	s_waitcnt lgkmcnt(2)
	v_cvt_pk_bf16_f32 v4, v18, v20
	s_waitcnt lgkmcnt(0)
	v_cvt_pk_bf16_f32 v5, v22, v24
	v_lshl_add_u64 v[28:29], v[8:9], 0, v[28:29]
	v_add_u32_e32 v10, 8, v26
	global_store_dwordx4 v[28:29], v[2:5], off
	v_add_u32_e32 v28, 16, v26
	v_ashrrev_i32_e32 v29, 31, v28
	v_cvt_pk_bf16_f32 v2, v13, v11
	v_ashrrev_i32_e32 v11, 31, v10
	v_lshlrev_b64 v[10:11], 9, v[10:11]
	v_cvt_pk_bf16_f32 v3, v15, v17
	v_cvt_pk_bf16_f32 v4, v19, v21
	v_cvt_pk_bf16_f32 v5, v23, v25
	v_lshl_add_u64 v[10:11], v[8:9], 0, v[10:11]
	global_store_dwordx4 v[10:11], v[2:5], off
	ds_read2_b32 v[10:11], v0 offset0:49 offset1:57
	ds_read2_b32 v[12:13], v0 offset0:16 offset1:24
	ds_read2_b32 v[14:15], v0 offset0:82 offset1:90
	ds_read2_b32 v[16:17], v0 offset0:115 offset1:123
	ds_read2_b32 v[18:19], v0 offset0:148 offset1:156
	ds_read2_b32 v[20:21], v0 offset0:181 offset1:189
	ds_read2_b32 v[22:23], v0 offset0:214 offset1:222
	ds_read2_b32 v[24:25], v0 offset0:247 offset1:255
	v_lshlrev_b64 v[28:29], 9, v[28:29]
	s_waitcnt lgkmcnt(6)
	v_cvt_pk_bf16_f32 v2, v12, v10
	s_waitcnt lgkmcnt(4)
	v_cvt_pk_bf16_f32 v3, v14, v16
	s_waitcnt lgkmcnt(2)
	v_cvt_pk_bf16_f32 v4, v18, v20
	s_waitcnt lgkmcnt(0)
	v_cvt_pk_bf16_f32 v5, v22, v24
	v_lshl_add_u64 v[28:29], v[8:9], 0, v[28:29]
	v_add_u32_e32 v10, 24, v26
	global_store_dwordx4 v[28:29], v[2:5], off
	s_nop 1
	v_cvt_pk_bf16_f32 v2, v13, v11
	v_ashrrev_i32_e32 v11, 31, v10
	v_lshlrev_b64 v[10:11], 9, v[10:11]
	v_cvt_pk_bf16_f32 v3, v15, v17
	v_cvt_pk_bf16_f32 v4, v19, v21
	v_cvt_pk_bf16_f32 v5, v23, v25
	v_lshl_add_u64 v[8:9], v[8:9], 0, v[10:11]
	global_store_dwordx4 v[8:9], v[2:5], off
	s_waitcnt lgkmcnt(0)

; __device__ __forceinline__ void conv_item(const float* W, int K, int Nsrc, int Ndst, const float* ksc, bf16* WT, int map, int item, LAS float* scr, int lane) {
;     ...
;     const int sc = src_col(map, n0 + (lane & 31));
;     float wv[32];
;     { const float* wp = W + (size_t)(k0 + (lane >> 5)) * Nsrc + (sc >= 0 ? sc : 0);
; #pragma unroll
;       for (int i = 0; i < 32; ++i) wv[i] = wp[(size_t)(2 * i) * Nsrc]; }
;     if (ksc) {
; #pragma unroll
;         for (int i = 0; i < 32; ++i) wv[i] *= ksc[k0 + 2 * i + (lane >> 5)];
.LBB0_476:
	s_and_b32 s0, 0xffff, s51
	v_ashrrev_i32_e32 v9, 5, v7
	v_and_b32_e32 v8, 31, v7
	v_lshl_add_u32 v2, s0, 6, v9
	v_mov_b64_e32 v[4:5], s[22:23]
	s_movk_i32 s1, 0xc00
	v_or_b32_e32 v0, s53, v8
	v_mad_i64_i32 v[4:5], s[52:53], v2, s1, v[4:5]
	v_lshl_add_u64 v[4:5], v[0:1], 2, v[4:5]
	v_add_co_u32_e32 v10, vcc, 0x1000, v4
	s_movk_i32 s1, 0x4000
	s_nop 0
	v_addc_co_u32_e32 v11, vcc, 0, v5, vcc
	global_load_dword v12, v[10:11], off offset:2048
	v_add_co_u32_e32 v10, vcc, 0x3000, v4
	global_load_dword v0, v[4:5], off
	s_nop 0
	v_addc_co_u32_e32 v11, vcc, 0, v5, vcc
	global_load_dword v13, v[10:11], off
	v_add_co_u32_e32 v10, vcc, s1, v4
	s_movk_i32 s1, 0x6000
	s_nop 0
	v_addc_co_u32_e32 v11, vcc, 0, v5, vcc
	global_load_dword v14, v[10:11], off offset:2048
	v_add_co_u32_e32 v10, vcc, s1, v4
	s_mov_b32 s1, 0xa000
	s_nop 0
	v_addc_co_u32_e32 v11, vcc, 0, v5, vcc
	global_load_dword v15, v[10:11], off
	v_add_co_u32_e32 v10, vcc, 0x7000, v4
	v_ashrrev_i32_e32 v3, 31, v2
	s_nop 0
	v_addc_co_u32_e32 v11, vcc, 0, v5, vcc
	global_load_dword v16, v[10:11], off offset:2048
	v_add_co_u32_e32 v10, vcc, 0x9000, v4
	v_lshl_add_u64 v[2:3], v[2:3], 2, s[24:25]
	s_nop 0
	v_addc_co_u32_e32 v11, vcc, 0, v5, vcc
	global_load_dword v17, v[10:11], off
	v_add_co_u32_e32 v10, vcc, s1, v4
	s_mov_b32 s1, 0xc000
	s_nop 0
	v_addc_co_u32_e32 v11, vcc, 0, v5, vcc
	global_load_dword v18, v[10:11], off offset:2048
	v_add_co_u32_e32 v10, vcc, s1, v4
	s_mov_b32 s1, 0x10000
	s_nop 0
	v_addc_co_u32_e32 v11, vcc, 0, v5, vcc
	global_load_dword v19, v[10:11], off
	v_add_co_u32_e32 v10, vcc, 0xd000, v4
	s_lshl_b32 s0, s0, 7
	s_nop 0
	v_addc_co_u32_e32 v11, vcc, 0, v5, vcc
	global_load_dword v20, v[10:11], off offset:2048
	v_add_co_u32_e32 v10, vcc, 0xf000, v4
	s_add_u32 s0, s58, s0
	s_nop 0
	v_addc_co_u32_e32 v11, vcc, 0, v5, vcc
	global_load_dword v21, v[10:11], off
	v_add_co_u32_e32 v10, vcc, s1, v4
	s_mov_b32 s1, 0x12000
	s_nop 0
	v_addc_co_u32_e32 v11, vcc, 0, v5, vcc
	global_load_dword v22, v[10:11], off offset:2048
	v_add_co_u32_e32 v10, vcc, s1, v4
	s_mov_b32 s1, 0x16000
	s_nop 0
	v_addc_co_u32_e32 v11, vcc, 0, v5, vcc
	global_load_dword v23, v[10:11], off
	v_add_co_u32_e32 v10, vcc, 0x13000, v4
	s_movk_i32 s27, 0x300
	s_nop 0
	v_addc_co_u32_e32 v11, vcc, 0, v5, vcc
	global_load_dword v24, v[10:11], off offset:2048
	v_add_co_u32_e32 v10, vcc, 0x15000, v4
	s_nop 1
	v_addc_co_u32_e32 v11, vcc, 0, v5, vcc
	global_load_dword v25, v[10:11], off
	v_add_co_u32_e32 v10, vcc, s1, v4
	s_mov_b32 s1, 0x18000
	s_nop 0
	v_addc_co_u32_e32 v11, vcc, 0, v5, vcc
	global_load_dword v26, v[10:11], off offset:2048
	v_add_co_u32_e32 v10, vcc, s1, v4
	s_mov_b32 s1, 0x1c000
	s_nop 0
	v_addc_co_u32_e32 v11, vcc, 0, v5, vcc
	global_load_dword v27, v[10:11], off
	v_add_co_u32_e32 v10, vcc, 0x19000, v4
	s_nop 1
	v_addc_co_u32_e32 v11, vcc, 0, v5, vcc
	global_load_dword v28, v[10:11], off offset:2048
	v_add_co_u32_e32 v10, vcc, 0x1b000, v4
	s_nop 1
	v_addc_co_u32_e32 v11, vcc, 0, v5, vcc
	global_load_dword v29, v[10:11], off
	v_add_co_u32_e32 v10, vcc, s1, v4
	s_mov_b32 s1, 0x1e000
	s_nop 0
	v_addc_co_u32_e32 v11, vcc, 0, v5, vcc
	global_load_dword v30, v[10:11], off offset:2048
	v_add_co_u32_e32 v10, vcc, s1, v4
	s_mov_b32 s1, 0x22000
	s_nop 0
	v_addc_co_u32_e32 v11, vcc, 0, v5, vcc
	global_load_dword v31, v[10:11], off
	v_add_co_u32_e32 v10, vcc, 0x1f000, v4
	s_nop 1
	v_addc_co_u32_e32 v11, vcc, 0, v5, vcc
	global_load_dword v32, v[10:11], off offset:2048
	v_add_co_u32_e32 v10, vcc, 0x21000, v4
	s_nop 1
	v_addc_co_u32_e32 v11, vcc, 0, v5, vcc
	global_load_dword v33, v[10:11], off
	v_add_co_u32_e32 v10, vcc, s1, v4
	s_mov_b32 s1, 0x24000
	s_nop 0
	v_addc_co_u32_e32 v11, vcc, 0, v5, vcc
	global_load_dword v34, v[10:11], off offset:2048
	v_add_co_u32_e32 v10, vcc, s1, v4
	s_mov_b32 s1, 0x28000
	s_nop 0
	v_addc_co_u32_e32 v11, vcc, 0, v5, vcc
	global_load_dword v35, v[10:11], off
	v_add_co_u32_e32 v10, vcc, 0x25000, v4
	s_nop 1
	v_addc_co_u32_e32 v11, vcc, 0, v5, vcc
	global_load_dword v36, v[10:11], off offset:2048
	v_add_co_u32_e32 v10, vcc, 0x27000, v4
	s_nop 1
	v_addc_co_u32_e32 v11, vcc, 0, v5, vcc
	global_load_dword v37, v[10:11], off
	v_add_co_u32_e32 v10, vcc, s1, v4
	s_mov_b32 s1, 0x2a000
	s_nop 0
	v_addc_co_u32_e32 v11, vcc, 0, v5, vcc
	global_load_dword v38, v[10:11], off offset:2048
	v_add_co_u32_e32 v10, vcc, s1, v4
	s_mov_b32 s1, 0x2e000
	s_nop 0
	v_addc_co_u32_e32 v11, vcc, 0, v5, vcc
	global_load_dword v39, v[10:11], off
	v_add_co_u32_e32 v10, vcc, 0x2b000, v4
	s_nop 1
	v_addc_co_u32_e32 v11, vcc, 0, v5, vcc
	global_load_dword v40, v[10:11], off offset:2048
	v_add_co_u32_e32 v10, vcc, 0x2d000, v4
	s_nop 1
	v_addc_co_u32_e32 v11, vcc, 0, v5, vcc
	v_add_co_u32_e32 v4, vcc, s1, v4
	global_load_dword v10, v[10:11], off
	s_nop 0
	v_addc_co_u32_e32 v5, vcc, 0, v5, vcc
	global_load_dword v4, v[4:5], off offset:2048
	s_movk_i32 s1, 0x84
	global_load_dword v64, v[2:3], off
	global_load_dword v65, v[2:3], off offset:16
	global_load_dword v66, v[2:3], off offset:8
	global_load_dword v67, v[2:3], off offset:32
	global_load_dword v68, v[2:3], off offset:24
	global_load_dword v69, v[2:3], off offset:48
	global_load_dword v70, v[2:3], off offset:40
	global_load_dword v71, v[2:3], off offset:64
	global_load_dword v72, v[2:3], off offset:56
	global_load_dword v73, v[2:3], off offset:80
	global_load_dword v74, v[2:3], off offset:72
	global_load_dword v75, v[2:3], off offset:96
	global_load_dword v76, v[2:3], off offset:88
	global_load_dword v77, v[2:3], off offset:112
	global_load_dword v78, v[2:3], off offset:104
	global_load_dword v79, v[2:3], off offset:128
	global_load_dword v80, v[2:3], off offset:120
	global_load_dword v81, v[2:3], off offset:144
	global_load_dword v82, v[2:3], off offset:136
	global_load_dword v83, v[2:3], off offset:160
	global_load_dword v84, v[2:3], off offset:152
	global_load_dword v85, v[2:3], off offset:176
	global_load_dword v86, v[2:3], off offset:168
	global_load_dword v87, v[2:3], off offset:192
	global_load_dword v88, v[2:3], off offset:184
	global_load_dword v89, v[2:3], off offset:208
	global_load_dword v90, v[2:3], off offset:200
	global_load_dword v91, v[2:3], off offset:224
	global_load_dword v92, v[2:3], off offset:216
	global_load_dword v93, v[2:3], off offset:240
	global_load_dword v94, v[2:3], off offset:232
	global_load_dword v95, v[2:3], off offset:248
	s_waitcnt vmcnt(31)
; #define LAS __attribute__((address_space(3)))
; __device__ __forceinline__ unsigned pk2(float lo, float hi) { f32x2 v = {lo, hi}; bf16x2_t b = __builtin_convertvector(v, bf16x2_t); return __builtin_bit_cast(unsigned, b); }
; __device__ __forceinline__ void conv_item(const float* W, int K, int Nsrc, int Ndst, const float* ksc, bf16* WT, int map, int item, LAS float* scr, int lane) {
;     ...
;         for (int i = 0; i < 32; ++i) wv[i] *= ksc[k0 + 2 * i + (lane >> 5)];
;     }
; #pragma unroll
;     for (int i = 0; i < 32; ++i) scr[(2 * i + (lane >> 5)) * 33 + (lane & 31)] = (sc >= 0) ? wv[i] : 0.f;
;     asm volatile("s_waitcnt lgkmcnt(0)" ::: "memory");
;     const int c = lane & 7;
; #pragma unroll
;     for (int j = 0; j < 4; ++j) { const int n = (lane >> 3) + 8 * j; const LAS float* s = scr + (8 * c) * 33 + n;
;         u32x4 o; o.x = pk2(s[0 * 33], s[1 * 33]); o.y = pk2(s[2 * 33], s[3 * 33]); o.z = pk2(s[4 * 33], s[5 * 33]); o.w = pk2(s[6 * 33], s[7 * 33]);
;         *(u32x4*)(WT + (size_t)(n0 + n) * K + k0 + 8 * c) = o; }
;     asm volatile("s_waitcnt lgkmcnt(0)" ::: "memory");
	v_mul_f32_e32 v0, v0, v64
	s_waitcnt vmcnt(30)
	v_mul_f32_e32 v11, v13, v65
	s_waitcnt vmcnt(29)
	v_mul_f32_e32 v5, v12, v66
	s_waitcnt vmcnt(28)
	v_mul_f32_e32 v13, v15, v67
	s_waitcnt vmcnt(27)
	v_mul_f32_e32 v12, v14, v68
	s_waitcnt vmcnt(26)
	v_mul_f32_e32 v15, v17, v69
	s_waitcnt vmcnt(25)
	v_mul_f32_e32 v14, v16, v70
	s_waitcnt vmcnt(24)
	v_mul_f32_e32 v17, v19, v71
	s_waitcnt vmcnt(23)
	v_mul_f32_e32 v16, v18, v72
	s_waitcnt vmcnt(22)
	v_mul_f32_e32 v19, v21, v73
	s_waitcnt vmcnt(21)
	v_mul_f32_e32 v18, v20, v74
	s_waitcnt vmcnt(20)
	v_mul_f32_e32 v21, v23, v75
	s_waitcnt vmcnt(19)
	v_mul_f32_e32 v20, v22, v76
	s_waitcnt vmcnt(18)
	v_mul_f32_e32 v23, v25, v77
	s_waitcnt vmcnt(17)
	v_mul_f32_e32 v22, v24, v78
	s_waitcnt vmcnt(16)
	v_mul_f32_e32 v25, v27, v79
	s_waitcnt vmcnt(15)
	v_mul_f32_e32 v24, v26, v80
	s_waitcnt vmcnt(14)
	v_mul_f32_e32 v27, v29, v81
	s_waitcnt vmcnt(13)
	v_mul_f32_e32 v26, v28, v82
	s_waitcnt vmcnt(12)
	v_mul_f32_e32 v29, v31, v83
	s_waitcnt vmcnt(11)
	v_mul_f32_e32 v28, v30, v84
	s_waitcnt vmcnt(10)
	v_mul_f32_e32 v31, v33, v85
	s_waitcnt vmcnt(9)
	v_mul_f32_e32 v30, v32, v86
	s_waitcnt vmcnt(8)
	v_mul_f32_e32 v33, v35, v87
	s_waitcnt vmcnt(7)
	v_mul_f32_e32 v32, v34, v88
	s_waitcnt vmcnt(6)
	v_mul_f32_e32 v35, v37, v89
	s_waitcnt vmcnt(5)
	v_mul_f32_e32 v34, v36, v90
	s_waitcnt vmcnt(4)
	v_mul_f32_e32 v37, v39, v91
	s_waitcnt vmcnt(3)
	v_mul_f32_e32 v36, v38, v92
	s_waitcnt vmcnt(2)
	v_mul_f32_e32 v10, v10, v93
	v_lshlrev_b32_e32 v3, 2, v8
	s_waitcnt vmcnt(1)
	v_mul_f32_e32 v38, v40, v94
	s_waitcnt vmcnt(0)
	v_mul_f32_e32 v2, v4, v95
	v_mul_lo_u32 v4, v9, s1
	v_add3_u32 v3, s56, v3, v4
	ds_write2_b32 v3, v0, v5 offset1:66
	ds_write2_b32 v3, v11, v12 offset0:132 offset1:198
	v_add_u32_e32 v0, 0x400, v3
	ds_write2_b32 v0, v13, v14 offset0:8 offset1:74
	ds_write2_b32 v0, v15, v16 offset0:140 offset1:206
	v_add_u32_e32 v0, 0x800, v3
	ds_write2_b32 v0, v17, v18 offset0:16 offset1:82
	ds_write2_b32 v0, v19, v20 offset0:148 offset1:214
	v_add_u32_e32 v0, 0xc00, v3
	ds_write2_b32 v0, v21, v22 offset0:24 offset1:90
	ds_write2_b32 v0, v23, v24 offset0:156 offset1:222
	v_add_u32_e32 v0, 0x1000, v3
	ds_write2_b32 v0, v25, v26 offset0:32 offset1:98
	ds_write2_b32 v0, v27, v28 offset0:164 offset1:230
	v_add_u32_e32 v0, 0x1400, v3
	ds_write2_b32 v0, v29, v30 offset0:40 offset1:106
	ds_write2_b32 v0, v31, v32 offset0:172 offset1:238
	v_add_u32_e32 v0, 0x1800, v3
	ds_write2_b32 v0, v33, v34 offset0:48 offset1:114
	ds_write2_b32 v0, v35, v36 offset0:180 offset1:246
	v_add_u32_e32 v0, 0x1c00, v3
	ds_write2_b32 v0, v37, v38 offset0:56 offset1:122
	ds_write2_b32 v0, v10, v2 offset0:188 offset1:254
	v_lshlrev_b32_e32 v0, 3, v7
	v_and_b32_e32 v0, 56, v0
	v_ashrrev_i32_e32 v26, 3, v7
	v_mul_u32_u24_e32 v4, 0x84, v0
	s_addc_u32 s1, s59, 0
	v_lshlrev_b32_e32 v0, 1, v0
	v_lshl_add_u64 v[2:3], s[0:1], 0, v[0:1]
	v_lshlrev_b32_e32 v0, 2, v26
	s_waitcnt lgkmcnt(0)
	v_add3_u32 v0, s56, v4, v0
	ds_read2_b32 v[10:11], v0 offset0:33 offset1:41
	ds_read2_b32 v[12:13], v0 offset1:8
	ds_read2_b32 v[14:15], v0 offset0:66 offset1:74
	ds_read2_b32 v[16:17], v0 offset0:99 offset1:107
	ds_read2_b32 v[18:19], v0 offset0:132 offset1:140
	ds_read2_b32 v[20:21], v0 offset0:165 offset1:173
	ds_read2_b32 v[22:23], v0 offset0:198 offset1:206
	ds_read2_b32 v[24:25], v0 offset0:231 offset1:239
	s_mov_b64 s[0:1], 0x1580000
	v_lshl_add_u64 v[8:9], v[2:3], 0, s[0:1]
	v_add_u32_e32 v28, s44, v26
	s_waitcnt lgkmcnt(6)
	v_cvt_pk_bf16_f32 v2, v12, v10
	s_waitcnt lgkmcnt(4)
	v_cvt_pk_bf16_f32 v3, v14, v16
	s_waitcnt lgkmcnt(2)
	v_cvt_pk_bf16_f32 v4, v18, v20
	s_waitcnt lgkmcnt(0)
	v_cvt_pk_bf16_f32 v5, v22, v24
	v_mad_i64_i32 v[26:27], s[0:1], v28, s27, v[8:9]
	v_add_u32_e32 v10, 8, v28
	global_store_dwordx4 v[26:27], v[2:5], off
	s_nop 1
	v_cvt_pk_bf16_f32 v2, v13, v11
	v_cvt_pk_bf16_f32 v3, v15, v17
	v_cvt_pk_bf16_f32 v4, v19, v21
	v_cvt_pk_bf16_f32 v5, v23, v25
	v_mad_i64_i32 v[10:11], s[0:1], v10, s27, v[8:9]
	global_store_dwordx4 v[10:11], v[2:5], off
	ds_read2_b32 v[10:11], v0 offset0:49 offset1:57
	ds_read2_b32 v[12:13], v0 offset0:16 offset1:24
	ds_read2_b32 v[14:15], v0 offset0:82 offset1:90
	ds_read2_b32 v[16:17], v0 offset0:115 offset1:123
	ds_read2_b32 v[18:19], v0 offset0:148 offset1:156
	ds_read2_b32 v[20:21], v0 offset0:181 offset1:189
	ds_read2_b32 v[22:23], v0 offset0:214 offset1:222
	ds_read2_b32 v[24:25], v0 offset0:247 offset1:255
	v_add_u32_e32 v0, 16, v28
	s_waitcnt lgkmcnt(6)
	v_cvt_pk_bf16_f32 v2, v12, v10
	s_waitcnt lgkmcnt(4)
	v_cvt_pk_bf16_f32 v3, v14, v16
	s_waitcnt lgkmcnt(2)
	v_cvt_pk_bf16_f32 v4, v18, v20
	s_waitcnt lgkmcnt(0)
	v_cvt_pk_bf16_f32 v5, v22, v24
	v_mad_i64_i32 v[26:27], s[0:1], v0, s27, v[8:9]
	v_add_u32_e32 v0, 24, v28
	global_store_dwordx4 v[26:27], v[2:5], off
	v_mad_i64_i32 v[8:9], s[0:1], v0, s27, v[8:9]
	s_nop 0
	v_cvt_pk_bf16_f32 v2, v13, v11
	v_cvt_pk_bf16_f32 v3, v15, v17
	v_cvt_pk_bf16_f32 v4, v19, v21
	v_cvt_pk_bf16_f32 v5, v23, v25
	global_store_dwordx4 v[8:9], v[2:5], off
	s_waitcnt lgkmcnt(0)

; __device__ __forceinline__ void conv_item(const float* W, int K, int Nsrc, int Ndst, const float* ksc, bf16* WT, int map, int item, LAS float* scr, int lane) {
;     ...
;     const int sc = src_col(map, n0 + (lane & 31));
;     float wv[32];
;     { const float* wp = W + (size_t)(k0 + (lane >> 5)) * Nsrc + (sc >= 0 ? sc : 0);
; #pragma unroll
;       for (int i = 0; i < 32; ++i) wv[i] = wp[(size_t)(2 * i) * Nsrc]; }
;     if (ksc) {
; #pragma unroll
;         for (int i = 0; i < 32; ++i) wv[i] *= ksc[k0 + 2 * i + (lane >> 5)];
.LBB0_513:
	s_or_b64 exec, exec, s[0:1]
	s_lshl_b32 s50, s60, 6
	v_ashrrev_i32_e32 v9, 5, v7
	v_add_u32_e32 v2, s50, v9
	v_mov_b64_e32 v[10:11], s[6:7]
	s_movk_i32 s0, 0x6aa0
	v_mad_i64_i32 v[10:11], s[0:1], v2, s0, v[10:11]
	v_cmp_lt_i32_e64 s[0:1], -1, v4
	s_mov_b32 s27, 0x1a000
	v_ashrrev_i32_e32 v3, 31, v2
	v_cndmask_b32_e64 v0, 0, v4, s[0:1]
	v_lshl_add_u64 v[4:5], v[0:1], 2, v[10:11]
	v_add_co_u32_e32 v10, vcc, 0xd000, v4
	global_load_dword v0, v[4:5], off
	s_nop 0
	v_addc_co_u32_e32 v11, vcc, 0, v5, vcc
	global_load_dword v12, v[10:11], off offset:1344
	v_add_co_u32_e32 v10, vcc, s27, v4
	v_lshl_add_u64 v[2:3], v[2:3], 2, s[20:21]
	s_nop 0
	v_addc_co_u32_e32 v11, vcc, 0, v5, vcc
	global_load_dword v13, v[10:11], off offset:2688
	v_add_co_u32_e32 v10, vcc, 0x27000, v4
	s_movk_i32 s27, 0x84
	s_nop 0
	v_addc_co_u32_e32 v11, vcc, 0, v5, vcc
	global_load_dword v14, v[10:11], off offset:4032
	v_add_co_u32_e32 v10, vcc, 0x35000, v4
	s_ashr_i32 s51, s50, 31
	s_nop 0
	v_addc_co_u32_e32 v11, vcc, 0, v5, vcc
	global_load_dword v15, v[10:11], off offset:1280
	v_add_co_u32_e32 v10, vcc, 0x42000, v4
	s_nop 1
	v_addc_co_u32_e32 v11, vcc, 0, v5, vcc
	global_load_dword v16, v[10:11], off offset:2624
	v_add_co_u32_e32 v10, vcc, 0x4f000, v4
	s_nop 1
	v_addc_co_u32_e32 v11, vcc, 0, v5, vcc
	global_load_dword v17, v[10:11], off offset:3968
	v_add_co_u32_e32 v10, vcc, 0x5d000, v4
	s_nop 1
	v_addc_co_u32_e32 v11, vcc, 0, v5, vcc
	global_load_dword v18, v[10:11], off offset:1216
	v_add_co_u32_e32 v10, vcc, 0x6a000, v4
	s_nop 1
	v_addc_co_u32_e32 v11, vcc, 0, v5, vcc
	global_load_dword v19, v[10:11], off offset:2560
	v_add_co_u32_e32 v10, vcc, 0x77000, v4
	s_nop 1
	v_addc_co_u32_e32 v11, vcc, 0, v5, vcc
	global_load_dword v20, v[10:11], off offset:3904
	v_add_co_u32_e32 v10, vcc, 0x85000, v4
	s_nop 1
	v_addc_co_u32_e32 v11, vcc, 0, v5, vcc
	global_load_dword v21, v[10:11], off offset:1152
	v_add_co_u32_e32 v10, vcc, 0x92000, v4
	s_nop 1
	v_addc_co_u32_e32 v11, vcc, 0, v5, vcc
	global_load_dword v22, v[10:11], off offset:2496
	v_add_co_u32_e32 v10, vcc, 0x9f000, v4
	s_nop 1
	v_addc_co_u32_e32 v11, vcc, 0, v5, vcc
	global_load_dword v23, v[10:11], off offset:3840
	v_add_co_u32_e32 v10, vcc, 0xad000, v4
	s_nop 1
	v_addc_co_u32_e32 v11, vcc, 0, v5, vcc
	global_load_dword v24, v[10:11], off offset:1088
	v_add_co_u32_e32 v10, vcc, 0xba000, v4
	s_nop 1
	v_addc_co_u32_e32 v11, vcc, 0, v5, vcc
	global_load_dword v25, v[10:11], off offset:2432
	v_add_co_u32_e32 v10, vcc, 0xc7000, v4
	s_nop 1
	v_addc_co_u32_e32 v11, vcc, 0, v5, vcc
	global_load_dword v26, v[10:11], off offset:3776
	v_add_co_u32_e32 v10, vcc, 0xd5000, v4
	s_nop 1
	v_addc_co_u32_e32 v11, vcc, 0, v5, vcc
	global_load_dword v27, v[10:11], off offset:1024
	v_add_co_u32_e32 v10, vcc, 0xe2000, v4
	s_nop 1
	v_addc_co_u32_e32 v11, vcc, 0, v5, vcc
	global_load_dword v28, v[10:11], off offset:2368
	v_add_co_u32_e32 v10, vcc, 0xef000, v4
	s_nop 1
	v_addc_co_u32_e32 v11, vcc, 0, v5, vcc
	global_load_dword v29, v[10:11], off offset:3712
	v_add_co_u32_e32 v10, vcc, 0xfd000, v4
	s_nop 1
	v_addc_co_u32_e32 v11, vcc, 0, v5, vcc
	global_load_dword v30, v[10:11], off offset:960
	v_add_co_u32_e32 v10, vcc, 0x10a000, v4
	s_nop 1
	v_addc_co_u32_e32 v11, vcc, 0, v5, vcc
	global_load_dword v31, v[10:11], off offset:2304
	v_add_co_u32_e32 v10, vcc, 0x117000, v4
	s_nop 1
	v_addc_co_u32_e32 v11, vcc, 0, v5, vcc
	global_load_dword v32, v[10:11], off offset:3648
	v_add_co_u32_e32 v10, vcc, 0x125000, v4
	s_nop 1
	v_addc_co_u32_e32 v11, vcc, 0, v5, vcc
	global_load_dword v33, v[10:11], off offset:896
	v_add_co_u32_e32 v10, vcc, 0x132000, v4
	s_nop 1
	v_addc_co_u32_e32 v11, vcc, 0, v5, vcc
	global_load_dword v34, v[10:11], off offset:2240
	v_add_co_u32_e32 v10, vcc, 0x13f000, v4
	s_nop 1
	v_addc_co_u32_e32 v11, vcc, 0, v5, vcc
	global_load_dword v35, v[10:11], off offset:3584
	v_add_co_u32_e32 v10, vcc, 0x14d000, v4
	s_nop 1
	v_addc_co_u32_e32 v11, vcc, 0, v5, vcc
	global_load_dword v36, v[10:11], off offset:832
	v_add_co_u32_e32 v10, vcc, 0x15a000, v4
	s_nop 1
	v_addc_co_u32_e32 v11, vcc, 0, v5, vcc
	global_load_dword v37, v[10:11], off offset:2176
	v_add_co_u32_e32 v10, vcc, 0x167000, v4
	s_nop 1
	v_addc_co_u32_e32 v11, vcc, 0, v5, vcc
	global_load_dword v38, v[10:11], off offset:3520
	v_add_co_u32_e32 v10, vcc, 0x175000, v4
	s_nop 1
	v_addc_co_u32_e32 v11, vcc, 0, v5, vcc
	global_load_dword v39, v[10:11], off offset:768
	v_add_co_u32_e32 v10, vcc, 0x182000, v4
	s_nop 1
	v_addc_co_u32_e32 v11, vcc, 0, v5, vcc
	global_load_dword v40, v[10:11], off offset:2112
	v_add_co_u32_e32 v10, vcc, 0x18f000, v4
	s_nop 1
	v_addc_co_u32_e32 v11, vcc, 0, v5, vcc
	v_add_co_u32_e32 v4, vcc, 0x19d000, v4
	global_load_dword v10, v[10:11], off offset:3456
	s_nop 0
	v_addc_co_u32_e32 v5, vcc, 0, v5, vcc
	global_load_dword v4, v[4:5], off offset:704
	s_nop 0
	global_load_dword v64, v[2:3], off
	global_load_dword v65, v[2:3], off offset:16
	global_load_dword v66, v[2:3], off offset:8
	global_load_dword v67, v[2:3], off offset:32
	global_load_dword v68, v[2:3], off offset:24
	global_load_dword v69, v[2:3], off offset:48
	global_load_dword v70, v[2:3], off offset:40
	global_load_dword v71, v[2:3], off offset:64
	global_load_dword v72, v[2:3], off offset:56
	global_load_dword v73, v[2:3], off offset:80
	global_load_dword v74, v[2:3], off offset:72
	global_load_dword v75, v[2:3], off offset:96
	global_load_dword v76, v[2:3], off offset:88
	global_load_dword v77, v[2:3], off offset:112
	global_load_dword v78, v[2:3], off offset:104
	global_load_dword v79, v[2:3], off offset:128
	global_load_dword v80, v[2:3], off offset:120
	global_load_dword v81, v[2:3], off offset:144
	global_load_dword v82, v[2:3], off offset:136
	global_load_dword v83, v[2:3], off offset:160
	global_load_dword v84, v[2:3], off offset:152
	global_load_dword v85, v[2:3], off offset:176
	global_load_dword v86, v[2:3], off offset:168
	global_load_dword v87, v[2:3], off offset:192
	global_load_dword v88, v[2:3], off offset:184
	global_load_dword v89, v[2:3], off offset:208
	global_load_dword v90, v[2:3], off offset:200
	global_load_dword v91, v[2:3], off offset:224
	global_load_dword v92, v[2:3], off offset:216
	global_load_dword v93, v[2:3], off offset:240
	global_load_dword v94, v[2:3], off offset:232
	global_load_dword v95, v[2:3], off offset:248
	s_waitcnt vmcnt(31)
; #define LAS __attribute__((address_space(3)))
; __device__ __forceinline__ unsigned pk2(float lo, float hi) { f32x2 v = {lo, hi}; bf16x2_t b = __builtin_convertvector(v, bf16x2_t); return __builtin_bit_cast(unsigned, b); }
; __device__ __forceinline__ void conv_item(const float* W, int K, int Nsrc, int Ndst, const float* ksc, bf16* WT, int map, int item, LAS float* scr, int lane) {
;     ...
;         for (int i = 0; i < 32; ++i) wv[i] *= ksc[k0 + 2 * i + (lane >> 5)];
;     }
; #pragma unroll
;     for (int i = 0; i < 32; ++i) scr[(2 * i + (lane >> 5)) * 33 + (lane & 31)] = (sc >= 0) ? wv[i] : 0.f;
;     asm volatile("s_waitcnt lgkmcnt(0)" ::: "memory");
;     const int c = lane & 7;
; #pragma unroll
;     for (int j = 0; j < 4; ++j) { const int n = (lane >> 3) + 8 * j; const LAS float* s = scr + (8 * c) * 33 + n;
;         u32x4 o; o.x = pk2(s[0 * 33], s[1 * 33]); o.y = pk2(s[2 * 33], s[3 * 33]); o.z = pk2(s[4 * 33], s[5 * 33]); o.w = pk2(s[6 * 33], s[7 * 33]);
;         *(u32x4*)(WT + (size_t)(n0 + n) * K + k0 + 8 * c) = o; }
;     asm volatile("s_waitcnt lgkmcnt(0)" ::: "memory");
	v_mul_f32_e32 v0, v0, v64
	s_waitcnt vmcnt(30)
	v_mul_f32_e32 v11, v13, v65
	v_cndmask_b32_e64 v0, 0, v0, s[0:1]
	s_waitcnt vmcnt(29)
	v_mul_f32_e32 v5, v12, v66
	s_waitcnt vmcnt(28)
	v_mul_f32_e32 v13, v15, v67
	s_waitcnt vmcnt(27)
	v_mul_f32_e32 v12, v14, v68
	s_waitcnt vmcnt(26)
	v_mul_f32_e32 v15, v17, v69
	s_waitcnt vmcnt(25)
	v_mul_f32_e32 v14, v16, v70
	s_waitcnt vmcnt(24)
	v_mul_f32_e32 v17, v19, v71
	s_waitcnt vmcnt(23)
	v_mul_f32_e32 v16, v18, v72
	s_waitcnt vmcnt(22)
	v_mul_f32_e32 v19, v21, v73
	s_waitcnt vmcnt(21)
	v_mul_f32_e32 v18, v20, v74
	s_waitcnt vmcnt(20)
	v_mul_f32_e32 v21, v23, v75
	s_waitcnt vmcnt(19)
	v_mul_f32_e32 v20, v22, v76
	s_waitcnt vmcnt(18)
	v_mul_f32_e32 v23, v25, v77
	s_waitcnt vmcnt(17)
	v_mul_f32_e32 v22, v24, v78
	s_waitcnt vmcnt(16)
	v_mul_f32_e32 v25, v27, v79
	s_waitcnt vmcnt(15)
	v_mul_f32_e32 v24, v26, v80
	s_waitcnt vmcnt(14)
	v_mul_f32_e32 v27, v29, v81
	s_waitcnt vmcnt(13)
	v_mul_f32_e32 v26, v28, v82
	s_waitcnt vmcnt(12)
	v_mul_f32_e32 v29, v31, v83
	s_waitcnt vmcnt(11)
	v_mul_f32_e32 v28, v30, v84
	s_waitcnt vmcnt(10)
	v_mul_f32_e32 v31, v33, v85
	s_waitcnt vmcnt(9)
	v_mul_f32_e32 v30, v32, v86
	s_waitcnt vmcnt(8)
	v_mul_f32_e32 v33, v35, v87
	s_waitcnt vmcnt(7)
	v_mul_f32_e32 v32, v34, v88
	s_waitcnt vmcnt(6)
	v_mul_f32_e32 v35, v37, v89
	s_waitcnt vmcnt(5)
	v_mul_f32_e32 v34, v36, v90
	s_waitcnt vmcnt(4)
	v_mul_f32_e32 v37, v39, v91
	s_waitcnt vmcnt(3)
	v_mul_f32_e32 v36, v38, v92
	s_waitcnt vmcnt(2)
	v_mul_f32_e32 v10, v10, v93
	v_lshlrev_b32_e32 v3, 2, v8
	s_waitcnt vmcnt(1)
	v_mul_f32_e32 v38, v40, v94
	s_waitcnt vmcnt(0)
	v_mul_f32_e32 v2, v4, v95
	v_mul_lo_u32 v4, v9, s27
	v_add3_u32 v3, s56, v3, v4
	v_cndmask_b32_e64 v4, 0, v5, s[0:1]
	ds_write2_b32 v3, v0, v4 offset1:66
	v_cndmask_b32_e64 v0, 0, v11, s[0:1]
	v_cndmask_b32_e64 v4, 0, v12, s[0:1]
	ds_write2_b32 v3, v0, v4 offset0:132 offset1:198
	v_cndmask_b32_e64 v0, 0, v13, s[0:1]
	v_cndmask_b32_e64 v4, 0, v14, s[0:1]
	v_add_u32_e32 v5, 0x400, v3
	ds_write2_b32 v5, v0, v4 offset0:8 offset1:74
	v_cndmask_b32_e64 v0, 0, v15, s[0:1]
	v_cndmask_b32_e64 v4, 0, v16, s[0:1]
	ds_write2_b32 v5, v0, v4 offset0:140 offset1:206
	v_cndmask_b32_e64 v0, 0, v17, s[0:1]
	v_cndmask_b32_e64 v4, 0, v18, s[0:1]
	v_add_u32_e32 v5, 0x800, v3
	ds_write2_b32 v5, v0, v4 offset0:16 offset1:82
	v_cndmask_b32_e64 v0, 0, v19, s[0:1]
	v_cndmask_b32_e64 v4, 0, v20, s[0:1]
	ds_write2_b32 v5, v0, v4 offset0:148 offset1:214
	v_cndmask_b32_e64 v0, 0, v21, s[0:1]
	v_cndmask_b32_e64 v4, 0, v22, s[0:1]
	v_add_u32_e32 v5, 0xc00, v3
	ds_write2_b32 v5, v0, v4 offset0:24 offset1:90
	v_cndmask_b32_e64 v0, 0, v23, s[0:1]
	v_cndmask_b32_e64 v4, 0, v24, s[0:1]
	ds_write2_b32 v5, v0, v4 offset0:156 offset1:222
	v_cndmask_b32_e64 v0, 0, v25, s[0:1]
	v_cndmask_b32_e64 v4, 0, v26, s[0:1]
	v_add_u32_e32 v5, 0x1000, v3
	ds_write2_b32 v5, v0, v4 offset0:32 offset1:98
	v_cndmask_b32_e64 v0, 0, v27, s[0:1]
	v_cndmask_b32_e64 v4, 0, v28, s[0:1]
	ds_write2_b32 v5, v0, v4 offset0:164 offset1:230
	v_cndmask_b32_e64 v0, 0, v29, s[0:1]
	v_cndmask_b32_e64 v4, 0, v30, s[0:1]
	v_add_u32_e32 v5, 0x1400, v3
	ds_write2_b32 v5, v0, v4 offset0:40 offset1:106
	v_cndmask_b32_e64 v0, 0, v31, s[0:1]
	v_cndmask_b32_e64 v4, 0, v32, s[0:1]
	ds_write2_b32 v5, v0, v4 offset0:172 offset1:238
	v_cndmask_b32_e64 v0, 0, v33, s[0:1]
	v_cndmask_b32_e64 v4, 0, v34, s[0:1]
	v_add_u32_e32 v5, 0x1800, v3
	ds_write2_b32 v5, v0, v4 offset0:48 offset1:114
	v_cndmask_b32_e64 v0, 0, v35, s[0:1]
	v_cndmask_b32_e64 v4, 0, v36, s[0:1]
	ds_write2_b32 v5, v0, v4 offset0:180 offset1:246
	v_cndmask_b32_e64 v0, 0, v37, s[0:1]
	v_cndmask_b32_e64 v4, 0, v38, s[0:1]
	v_add_u32_e32 v3, 0x1c00, v3
	ds_write2_b32 v3, v0, v4 offset0:56 offset1:122
	v_cndmask_b32_e64 v0, 0, v10, s[0:1]
	v_cndmask_b32_e64 v2, 0, v2, s[0:1]
	ds_write2_b32 v3, v0, v2 offset0:188 offset1:254
	v_lshlrev_b32_e32 v0, 3, v7
	s_lshl_b64 s[0:1], s[50:51], 1
	v_and_b32_e32 v0, 56, v0
	s_add_u32 s0, s58, s0
	v_ashrrev_i32_e32 v26, 3, v7
	v_mul_u32_u24_e32 v4, 0x84, v0
	s_addc_u32 s1, s59, s1
	v_lshlrev_b32_e32 v0, 1, v0
	v_lshl_add_u64 v[2:3], s[0:1], 0, v[0:1]
	v_lshlrev_b32_e32 v0, 2, v26
	s_waitcnt lgkmcnt(0)
	v_add3_u32 v0, s56, v4, v0
	ds_read2_b32 v[10:11], v0 offset0:33 offset1:41
	ds_read2_b32 v[12:13], v0 offset1:8
	ds_read2_b32 v[14:15], v0 offset0:66 offset1:74
	ds_read2_b32 v[16:17], v0 offset0:99 offset1:107
	ds_read2_b32 v[18:19], v0 offset0:132 offset1:140
	ds_read2_b32 v[20:21], v0 offset0:165 offset1:173
	ds_read2_b32 v[22:23], v0 offset0:198 offset1:206
	ds_read2_b32 v[24:25], v0 offset0:231 offset1:239
	v_add_u32_e32 v26, s44, v26
	s_mov_b64 s[0:1], 0x800000
	v_ashrrev_i32_e32 v27, 31, v26
	v_lshl_add_u64 v[8:9], v[2:3], 0, s[0:1]
	v_lshlrev_b64 v[28:29], 11, v[26:27]
	s_waitcnt lgkmcnt(6)
	v_cvt_pk_bf16_f32 v2, v12, v10
	s_waitcnt lgkmcnt(4)
	v_cvt_pk_bf16_f32 v3, v14, v16
	s_waitcnt lgkmcnt(2)
	v_cvt_pk_bf16_f32 v4, v18, v20
	s_waitcnt lgkmcnt(0)
	v_cvt_pk_bf16_f32 v5, v22, v24
	v_lshl_add_u64 v[28:29], v[8:9], 0, v[28:29]
	v_add_u32_e32 v10, 8, v26
	global_store_dwordx4 v[28:29], v[2:5], off
	v_add_u32_e32 v28, 16, v26
	v_ashrrev_i32_e32 v29, 31, v28
	v_cvt_pk_bf16_f32 v2, v13, v11
	v_ashrrev_i32_e32 v11, 31, v10
	v_lshlrev_b64 v[10:11], 11, v[10:11]
	v_cvt_pk_bf16_f32 v3, v15, v17
	v_cvt_pk_bf16_f32 v4, v19, v21
	v_cvt_pk_bf16_f32 v5, v23, v25
	v_lshl_add_u64 v[10:11], v[8:9], 0, v[10:11]
	global_store_dwordx4 v[10:11], v[2:5], off
	ds_read2_b32 v[10:11], v0 offset0:49 offset1:57
	ds_read2_b32 v[12:13], v0 offset0:16 offset1:24
	ds_read2_b32 v[14:15], v0 offset0:82 offset1:90
	ds_read2_b32 v[16:17], v0 offset0:115 offset1:123
	ds_read2_b32 v[18:19], v0 offset0:148 offset1:156
	ds_read2_b32 v[20:21], v0 offset0:181 offset1:189
	ds_read2_b32 v[22:23], v0 offset0:214 offset1:222
	ds_read2_b32 v[24:25], v0 offset0:247 offset1:255
	v_lshlrev_b64 v[28:29], 11, v[28:29]
	s_waitcnt lgkmcnt(6)
	v_cvt_pk_bf16_f32 v2, v12, v10
	s_waitcnt lgkmcnt(4)
	v_cvt_pk_bf16_f32 v3, v14, v16
	s_waitcnt lgkmcnt(2)
	v_cvt_pk_bf16_f32 v4, v18, v20
	s_waitcnt lgkmcnt(0)
	v_cvt_pk_bf16_f32 v5, v22, v24
	v_lshl_add_u64 v[28:29], v[8:9], 0, v[28:29]
	v_add_u32_e32 v10, 24, v26
	global_store_dwordx4 v[28:29], v[2:5], off
	s_nop 1
	v_cvt_pk_bf16_f32 v2, v13, v11
	v_ashrrev_i32_e32 v11, 31, v10
	v_lshlrev_b64 v[10:11], 11, v[10:11]
	v_cvt_pk_bf16_f32 v3, v15, v17
	v_cvt_pk_bf16_f32 v4, v19, v21
	v_cvt_pk_bf16_f32 v5, v23, v25
	v_lshl_add_u64 v[8:9], v[8:9], 0, v[10:11]
	global_store_dwordx4 v[8:9], v[2:5], off
	s_waitcnt lgkmcnt(0)
	s_and_saveexec_b64 s[0:1], s[40:41]
	s_cbranch_execz .LBB0_441
